# P1 epilogue hand-written (straight-line per sub-tile, one uniform silu branch, wave-private LDS transposition without workgroup barriers, no accumulator shuffles) on top of hand-written GEMM loops + t
# baseline (speedup 1.0000x reference)
.LBB0_137:
	v_mov_b32_e32 v0, 0x1bf9c000
	global_load_dword v2, v0, s[90:91] offset:1024 sc1
	global_load_dword v3, v0, s[90:91] offset:1028 sc1
	global_load_dword v4, v0, s[90:91] offset:1032 sc1
	global_load_dword v5, v0, s[90:91] offset:1036 sc1
	global_load_dword v6, v0, s[90:91] offset:1040 sc1
	s_waitcnt lgkmcnt(0)
	global_load_dword v7, v0, s[90:91] offset:1044 sc1
	global_load_dword v8, v0, s[90:91] offset:1048 sc1
	global_load_dword v9, v0, s[90:91] offset:1052 sc1
	s_cmp_lt_i32 s8, 2
	s_cselect_b64 s[0:1], -1, 0
	s_cmp_gt_i32 s9, 1
	s_cselect_b64 s[2:3], -1, 0
	s_and_b64 s[0:1], s[0:1], s[2:3]
	s_andn2_b64 vcc, exec, s[0:1]
	v_cmp_lt_i32_e64 s[0:1], 0, v1
	s_waitcnt vmcnt(7)
	s_nop 0
	v_cndmask_b32_e64 v0, 0, v2, s[0:1]
	v_cmp_eq_u32_e64 s[0:1], 0, v1
	s_nop 1
	v_cndmask_b32_e64 v10, 0, v2, s[0:1]
	v_cmp_lt_i32_e64 s[0:1], 1, v1
	s_waitcnt vmcnt(6)
	s_nop 0
	v_cndmask_b32_e64 v11, 0, v3, s[0:1]
	v_cmp_lt_i32_e64 s[0:1], 0, v3
	s_nop 1
	v_cndmask_b32_e64 v12, 0, 1, s[0:1]
	v_cmp_lt_i32_e64 s[0:1], 2, v1
	s_waitcnt vmcnt(5)
	s_nop 0
	v_cndmask_b32_e64 v13, 0, v4, s[0:1]
	v_cmp_lt_i32_e64 s[0:1], 0, v4
	v_add3_u32 v0, v11, v0, v13
	s_nop 0
	v_cndmask_b32_e64 v14, 0, 1, s[0:1]
	v_cmp_lt_i32_e64 s[0:1], 3, v1
	s_waitcnt vmcnt(4)
	s_nop 0
	v_cndmask_b32_e64 v15, 0, v5, s[0:1]
	v_cmp_lt_i32_e64 s[0:1], 4, v1
	s_waitcnt vmcnt(3)
	s_nop 0
	v_cndmask_b32_e64 v16, 0, v6, s[0:1]
	v_cmp_lt_i32_e64 s[0:1], 0, v6
	v_add3_u32 v0, v15, v0, v16
	s_nop 0
	v_cndmask_b32_e64 v17, 0, 1, s[0:1]
	v_cmp_lt_i32_e64 s[0:1], 5, v1
	s_waitcnt vmcnt(2)
	s_nop 0
	v_cndmask_b32_e64 v18, 0, v7, s[0:1]
	v_cmp_lt_i32_e64 s[0:1], 6, v1
	s_waitcnt vmcnt(1)
	s_nop 0
	v_cndmask_b32_e64 v19, 0, v8, s[0:1]
	v_cmp_lt_i32_e64 s[0:1], 0, v8
	v_add3_u32 v0, v18, v0, v19
	s_nop 0
	v_cndmask_b32_e64 v20, 0, 1, s[0:1]
	v_cmp_lt_i32_e64 s[0:1], 7, v1
	s_waitcnt vmcnt(0)
	s_nop 0
	v_cndmask_b32_e64 v21, 0, v9, s[0:1]
	v_cmp_eq_u32_e64 s[0:1], 1, v1
	v_add3_u32 v200, v21, v0, v76
	v_lshl_or_b32 v197, v1, 9, v200
	v_cndmask_b32_e64 v3, v10, v3, s[0:1]
	v_cmp_lt_i32_e64 s[0:1], 0, v2
	v_bfe_u32 v199, v200, 6, 3
	v_and_b32_e32 v198, 63, v200
	v_addc_co_u32_e64 v2, s[0:1], 0, v12, s[0:1]
	v_cmp_eq_u32_e64 s[0:1], 2, v1
	s_nop 1
	v_cndmask_b32_e64 v3, v3, v4, s[0:1]
	v_cmp_lt_i32_e64 s[0:1], 0, v5
	s_nop 1
	v_addc_co_u32_e64 v2, s[0:1], v2, v14, s[0:1]
	v_cmp_eq_u32_e64 s[0:1], 3, v1
	s_nop 1
	v_cndmask_b32_e64 v3, v3, v5, s[0:1]
	v_cmp_lt_i32_e64 s[0:1], 0, v7
	s_nop 1
	v_addc_co_u32_e64 v2, s[0:1], v2, v17, s[0:1]
	v_cmp_eq_u32_e64 s[0:1], 4, v1
	s_nop 1
	v_cndmask_b32_e64 v3, v3, v6, s[0:1]
	v_cmp_lt_i32_e64 s[0:1], 0, v9
	s_nop 1
	v_addc_co_u32_e64 v2, s[0:1], v2, v20, s[0:1]
	v_cmp_eq_u32_e64 s[0:1], 5, v1
	v_lshlrev_b32_e32 v2, 22, v2
	s_nop 0
	v_cndmask_b32_e64 v0, v3, v7, s[0:1]
	v_cmp_eq_u32_e64 s[0:1], 6, v1
	s_nop 1
	v_cndmask_b32_e64 v0, v0, v8, s[0:1]
	v_cmp_eq_u32_e64 s[0:1], 7, v1
	s_nop 1
	v_cndmask_b32_e64 v0, v0, v9, s[0:1]
	v_lshlrev_b32_e32 v0, 12, v0
	v_or3_b32 v196, v0, v2, v197
	s_cbranch_vccnz .LBB0_299
	v_readlane_b32 s0, v254, 10
	s_lshr_b32 s0, s0, 6
	s_sub_i32 s1, 0, s0
	v_cvt_f32_u32_e32 v0, s0
	v_and_b32_e32 v145, 63, v200
	v_rcp_iflag_f32_e32 v1, v0
	v_bfe_u32 v0, v200, 6, 3
	v_cmp_eq_u32_e32 vcc, 0, v0
	v_mul_f32_e32 v1, 0x4f7ffffe, v1
	v_cvt_u32_f32_e32 v1, v1
	v_cndmask_b32_e64 v2, 0, 22, vcc
	v_readfirstlane_b32 s2, v1
	s_mul_i32 s1, s1, s2
	s_mul_hi_u32 s1, s2, s1
	s_add_i32 s2, s2, s1
	s_lshr_b32 s1, s2, 25
	s_mul_i32 s2, s1, s0
	s_sub_i32 s2, 0x80, s2
	s_add_i32 s3, s1, 1
	s_sub_i32 s4, s2, s0
	s_cmp_ge_u32 s2, s0
	s_cselect_b32 s1, s3, s1
	s_cselect_b32 s2, s4, s2
	s_add_i32 s3, s1, 1
	s_cmp_ge_u32 s2, s0
	s_cselect_b32 s2, s3, s1
	v_mad_u64_u32 v[140:141], s[0:1], s2, 22, v[2:3]
	v_cmp_lt_u32_e64 s[0:1], v145, v140
	s_and_saveexec_b64 s[6:7], s[0:1]
	s_cbranch_execz .LBB0_289
	s_add_u32 s8, s90, 0x1bf58000
	v_mul_u32_u24_e32 v201, s2, v0
	v_lshlrev_b32_e32 v0, 4, v144
	s_addc_u32 s9, s91, 0
	v_lshrrev_b32_e32 v1, 5, v144
	v_and_b32_e32 v8, 0x3c0, v0
	v_bitop3_b32 v9, v0, 48, v144 bitop3:0x48
	v_bfe_u32 v0, v144, 2, 2
	s_add_u32 s12, s90, 0x1ab88000
	v_bitop3_b32 v1, v1, v0, 1 bitop3:0x6c
	s_addc_u32 s13, s91, 0
	s_lshl_b32 s54, s2, 3
	v_lshlrev_b32_e32 v202, 4, v1
	v_lshlrev_b32_e32 v1, 3, v144
	v_and_b32_e32 v2, 56, v1
	v_cvt_f32_u32_e32 v1, s54
	v_lshrrev_b32_e32 v5, 6, v144
	v_lshlrev_b32_e32 v7, 10, v5
	v_and_b32_e32 v141, 31, v144
	v_rcp_iflag_f32_e32 v1, v1
	v_bfe_u32 v3, v144, 5, 1
	v_lshrrev_b32_e32 v4, 7, v144
	v_add_u32_e32 v204, 0, v7
	v_mul_f32_e32 v1, 0x4f7ffffe, v1
	v_cvt_u32_f32_e32 v1, v1
	s_movk_i32 s0, 0x1e00
	v_bitop3_b32 v0, v3, v0, 2 bitop3:0x36
	v_lshlrev_b32_e32 v205, 5, v4
	v_lshlrev_b32_e32 v212, 11, v4
	v_mad_u32_u24 v4, v5, s0, v204
	v_mul_u32_u24_e32 v5, 0x110, v141
	v_lshlrev_b32_e32 v3, 4, v3
	s_sub_i32 s0, 0, s54
	v_bfe_u32 v6, v144, 6, 1
	v_bfe_u32 v206, v144, 3, 3
	v_add3_u32 v213, v4, v5, v3
	v_mul_lo_u32 v5, s0, v1
	v_or3_b32 v142, v8, v9, v7
	v_lshlrev_b32_e32 v203, 4, v0
	v_lshlrev_b32_e32 v0, 6, v6
	v_mov_b32_e32 v147, 0
	v_lshlrev_b32_e32 v210, 12, v6
	v_lshlrev_b32_e32 v211, 6, v141
	v_lshl_add_u32 v3, v2, 2, v4
	v_mul_u32_u24_e32 v4, 0x110, v206
	v_mul_hi_u32 v5, v1, v5
	v_or3_b32 v150, v7, v8, v9
	s_mov_b64 s[10:11], 0x1ab88000
	v_or_b32_e32 v207, 8, v206
	v_or_b32_e32 v208, 16, v206
	v_or_b32_e32 v209, 24, v206
	v_mov_b32_e32 v143, v147
	v_add_u32_e32 v148, 0x1000, v142
	v_mov_b32_e32 v149, v147
	v_add3_u32 v214, 0, v210, v211
	v_add3_u32 v215, 0, v212, v211
	v_add_u32_e32 v216, v1, v5
	v_or_b32_e32 v152, 0xb0000, v150
	v_mov_b32_e32 v153, v147
	v_or_b32_e32 v154, 0x808000, v150
	v_mov_b32_e32 v155, v147
	v_mov_b32_e32 v151, v147
	v_or_b32_e32 v156, 0x58000, v150
	v_mov_b32_e32 v157, v147
	v_or_b32_e32 v158, 0x404000, v150
	v_mov_b32_e32 v159, v147
	v_or_b32_e32 v160, 0x84000, v150
	v_mov_b32_e32 v161, v147
	v_add_u32_e32 v162, 0x606000, v150
	v_mov_b32_e32 v163, v147
	s_mov_b64 s[14:15], 0
	s_mov_b64 s[16:17], 0x202000
	s_mov_b64 s[18:19], 0x2c000
	s_mov_b64 s[20:21], 0x1000
	s_mov_b64 s[22:23], 0x1ab89000
	s_mov_b64 s[24:25], 0x606000
	s_mov_b64 s[26:27], 0x1ac0d000
	s_mov_b64 s[28:29], 0x84000
	s_mov_b64 s[30:31], 0x2000
	s_mov_b64 s[34:35], 0x3000
	s_mov_b64 s[36:37], 0x204000
	s_mov_b64 s[38:39], 0x205000
	s_mov_b64 s[40:41], 0x404000
	s_mov_b64 s[42:43], 0x405000
	s_mov_b64 s[44:45], 0x406000
	s_mov_b64 s[46:47], 0x407000
	s_mov_b64 s[48:49], 0x1abe0000
	s_mov_b64 s[50:51], 0x1abe1000
	s_mov_b64 s[60:61], 0x58000
	v_lshlrev_b32_e32 v164, 1, v0
	v_lshlrev_b32_e32 v166, 1, v2
	s_movk_i32 s55, 0xb00
	v_mov_b32_e32 v217, 0x4040000
	v_mov_b32_e32 v218, 0x9898000
	v_add_u32_e32 v219, v3, v4
	s_branch .LBB0_142
.LBB0_141:
	s_or_b64 exec, exec, s[0:1]
	v_add_u32_e32 v145, 64, v145
	v_cmp_ge_u32_e64 s[0:1], v145, v140
	s_or_b64 s[14:15], s[0:1], s[14:15]
	s_barrier
	s_andn2_b64 exec, exec, s[14:15]
	s_cbranch_execz .LBB0_289

.LBB0_156:
	s_or_b64 exec, exec, s[0:1]
	v_readfirstlane_b32 s56, v170
	v_readfirstlane_b32 s57, v168
	v_readfirstlane_b32 s58, v204
	v_mbcnt_lo_u32_b32 v128, -1, 0
	v_mbcnt_hi_u32_b32 v128, -1, v128
	s_lshr_b32 s58, s58, 10
	s_and_b32 s59, s58, 1
	s_lshr_b32 s62, s58, 1
	s_lshl_b32 s63, s56, 8
	s_lshl_b32 s66, s62, 5
	s_add_u32 s63, s63, s66
	s_lshl_b32 s66, s63, 2
	s_add_u32 s64, s90, s66
	s_addc_u32 s65, s91, 0
	s_add_u32 s64, s64, 0x1bf58000
	s_addc_u32 s65, s65, 0
	v_and_b32_e32 v129, 31, v128
	v_lshlrev_b32_e32 v131, 2, v129
	global_load_dword v132, v131, s[64:65]
	global_load_dword v134, v131, s[64:65] offset:256
	global_load_dword v136, v131, s[64:65] offset:512
	global_load_dword v138, v131, s[64:65] offset:768
	s_cmp_ge_u32 s57, 11
	s_mov_b32 s67, 0x4040000
	s_cmov_b32 s67, 0x9898000
	s_cselect_b32 s68, 11, 0
	s_cselect_b32 s69, 1, 0
	s_sub_u32 s68, s57, s68
	s_lshl_b32 s68, s68, 8
	s_lshl_b32 s70, s59, 7
	s_add_u32 s68, s68, s70
	s_mul_i32 s70, s63, 0xb00
	s_add_u32 s68, s68, s70
	s_add_u32 s68, s68, s67
	s_add_u32 s66, s90, s68
	s_addc_u32 s67, s91, 0
	v_lshrrev_b32_e32 v130, 5, v128
	v_lshlrev_b32_e32 v130, 4, v130
	v_mul_u32_u24_e32 v129, 0x110, v129
	v_add_u32_e32 v129, v129, v130
	s_mul_i32 s70, s58, 0x2200
	v_add_u32_e32 v129, s70, v129
	v_lshrrev_b32_e32 v130, 3, v128
	v_and_b32_e32 v131, 7, v128
	v_mul_u32_u24_e32 v139, 0x110, v130
	v_lshl_add_u32 v139, v131, 5, v139
	v_add_u32_e32 v139, s70, v139
	v_mul_u32_u24_e32 v130, 0xb00, v130
	v_lshl_add_u32 v172, v131, 4, v130
	v_add_u32_e32 v173, 0x5800, v172
	v_add_u32_e32 v174, 0xb000, v172
	v_add_u32_e32 v175, 0x10800, v172
	s_waitcnt vmcnt(0) lgkmcnt(0)
	s_barrier
	v_pk_mul_f32 v[64:65], v[64:65], v[132:133] op_sel_hi:[1,0]
	v_pk_mul_f32 v[66:67], v[66:67], v[132:133] op_sel_hi:[1,0]
	v_pk_mul_f32 v[68:69], v[68:69], v[132:133] op_sel_hi:[1,0]
	v_pk_mul_f32 v[70:71], v[70:71], v[132:133] op_sel_hi:[1,0]
	v_pk_mul_f32 v[72:73], v[72:73], v[132:133] op_sel_hi:[1,0]
	v_pk_mul_f32 v[74:75], v[74:75], v[132:133] op_sel_hi:[1,0]
	v_pk_mul_f32 v[76:77], v[76:77], v[132:133] op_sel_hi:[1,0]
	v_pk_mul_f32 v[78:79], v[78:79], v[132:133] op_sel_hi:[1,0]
	v_pk_mul_f32 v[48:49], v[48:49], v[132:133] op_sel_hi:[1,0]
	v_pk_mul_f32 v[50:51], v[50:51], v[132:133] op_sel_hi:[1,0]
	v_pk_mul_f32 v[52:53], v[52:53], v[132:133] op_sel_hi:[1,0]
	v_pk_mul_f32 v[54:55], v[54:55], v[132:133] op_sel_hi:[1,0]
	v_pk_mul_f32 v[56:57], v[56:57], v[132:133] op_sel_hi:[1,0]
	v_pk_mul_f32 v[58:59], v[58:59], v[132:133] op_sel_hi:[1,0]
	v_pk_mul_f32 v[60:61], v[60:61], v[132:133] op_sel_hi:[1,0]
	v_pk_mul_f32 v[62:63], v[62:63], v[132:133] op_sel_hi:[1,0]
	s_cmp_eq_u32 s69, 0
	s_cbranch_scc1 .Le1_nosilu0
	v_mul_f32_e32 v176, 0xbfb8aa3b, v64
	v_mul_f32_e32 v177, 0xbfb8aa3b, v65
	v_mul_f32_e32 v178, 0xbfb8aa3b, v66
	v_mul_f32_e32 v179, 0xbfb8aa3b, v67
	v_mul_f32_e32 v180, 0xbfb8aa3b, v68
	v_mul_f32_e32 v181, 0xbfb8aa3b, v69
	v_mul_f32_e32 v182, 0xbfb8aa3b, v70
	v_mul_f32_e32 v183, 0xbfb8aa3b, v71
	v_exp_f32_e32 v176, v176
	v_exp_f32_e32 v177, v177
	v_exp_f32_e32 v178, v178
	v_exp_f32_e32 v179, v179
	v_exp_f32_e32 v180, v180
	v_exp_f32_e32 v181, v181
	v_exp_f32_e32 v182, v182
	v_exp_f32_e32 v183, v183
	v_add_f32_e32 v176, 1.0, v176
	v_add_f32_e32 v177, 1.0, v177
	v_add_f32_e32 v178, 1.0, v178
	v_add_f32_e32 v179, 1.0, v179
	v_add_f32_e32 v180, 1.0, v180
	v_add_f32_e32 v181, 1.0, v181
	v_add_f32_e32 v182, 1.0, v182
	v_add_f32_e32 v183, 1.0, v183
	v_rcp_f32_e32 v176, v176
	v_rcp_f32_e32 v177, v177
	v_rcp_f32_e32 v178, v178
	v_rcp_f32_e32 v179, v179
	v_rcp_f32_e32 v180, v180
	v_rcp_f32_e32 v181, v181
	v_rcp_f32_e32 v182, v182
	v_rcp_f32_e32 v183, v183
	v_mul_f32_e32 v64, v64, v176
	v_mul_f32_e32 v65, v65, v177
	v_mul_f32_e32 v66, v66, v178
	v_mul_f32_e32 v67, v67, v179
	v_mul_f32_e32 v68, v68, v180
	v_mul_f32_e32 v69, v69, v181
	v_mul_f32_e32 v70, v70, v182
	v_mul_f32_e32 v71, v71, v183
	v_mul_f32_e32 v176, 0xbfb8aa3b, v72
	v_mul_f32_e32 v177, 0xbfb8aa3b, v73
	v_mul_f32_e32 v178, 0xbfb8aa3b, v74
	v_mul_f32_e32 v179, 0xbfb8aa3b, v75
	v_mul_f32_e32 v180, 0xbfb8aa3b, v76
	v_mul_f32_e32 v181, 0xbfb8aa3b, v77
	v_mul_f32_e32 v182, 0xbfb8aa3b, v78
	v_mul_f32_e32 v183, 0xbfb8aa3b, v79
	v_exp_f32_e32 v176, v176
	v_exp_f32_e32 v177, v177
	v_exp_f32_e32 v178, v178
	v_exp_f32_e32 v179, v179
	v_exp_f32_e32 v180, v180
	v_exp_f32_e32 v181, v181
	v_exp_f32_e32 v182, v182
	v_exp_f32_e32 v183, v183
	v_add_f32_e32 v176, 1.0, v176
	v_add_f32_e32 v177, 1.0, v177
	v_add_f32_e32 v178, 1.0, v178
	v_add_f32_e32 v179, 1.0, v179
	v_add_f32_e32 v180, 1.0, v180
	v_add_f32_e32 v181, 1.0, v181
	v_add_f32_e32 v182, 1.0, v182
	v_add_f32_e32 v183, 1.0, v183
	v_rcp_f32_e32 v176, v176
	v_rcp_f32_e32 v177, v177
	v_rcp_f32_e32 v178, v178
	v_rcp_f32_e32 v179, v179
	v_rcp_f32_e32 v180, v180
	v_rcp_f32_e32 v181, v181
	v_rcp_f32_e32 v182, v182
	v_rcp_f32_e32 v183, v183
	v_mul_f32_e32 v72, v72, v176
	v_mul_f32_e32 v73, v73, v177
	v_mul_f32_e32 v74, v74, v178
	v_mul_f32_e32 v75, v75, v179
	v_mul_f32_e32 v76, v76, v180
	v_mul_f32_e32 v77, v77, v181
	v_mul_f32_e32 v78, v78, v182
	v_mul_f32_e32 v79, v79, v183
	v_mul_f32_e32 v176, 0xbfb8aa3b, v48
	v_mul_f32_e32 v177, 0xbfb8aa3b, v49
	v_mul_f32_e32 v178, 0xbfb8aa3b, v50
	v_mul_f32_e32 v179, 0xbfb8aa3b, v51
	v_mul_f32_e32 v180, 0xbfb8aa3b, v52
	v_mul_f32_e32 v181, 0xbfb8aa3b, v53
	v_mul_f32_e32 v182, 0xbfb8aa3b, v54
	v_mul_f32_e32 v183, 0xbfb8aa3b, v55
	v_exp_f32_e32 v176, v176
	v_exp_f32_e32 v177, v177
	v_exp_f32_e32 v178, v178
	v_exp_f32_e32 v179, v179
	v_exp_f32_e32 v180, v180
	v_exp_f32_e32 v181, v181
	v_exp_f32_e32 v182, v182
	v_exp_f32_e32 v183, v183
	v_add_f32_e32 v176, 1.0, v176
	v_add_f32_e32 v177, 1.0, v177
	v_add_f32_e32 v178, 1.0, v178
	v_add_f32_e32 v179, 1.0, v179
	v_add_f32_e32 v180, 1.0, v180
	v_add_f32_e32 v181, 1.0, v181
	v_add_f32_e32 v182, 1.0, v182
	v_add_f32_e32 v183, 1.0, v183
	v_rcp_f32_e32 v176, v176
	v_rcp_f32_e32 v177, v177
	v_rcp_f32_e32 v178, v178
	v_rcp_f32_e32 v179, v179
	v_rcp_f32_e32 v180, v180
	v_rcp_f32_e32 v181, v181
	v_rcp_f32_e32 v182, v182
	v_rcp_f32_e32 v183, v183
	v_mul_f32_e32 v48, v48, v176
	v_mul_f32_e32 v49, v49, v177
	v_mul_f32_e32 v50, v50, v178
	v_mul_f32_e32 v51, v51, v179
	v_mul_f32_e32 v52, v52, v180
	v_mul_f32_e32 v53, v53, v181
	v_mul_f32_e32 v54, v54, v182
	v_mul_f32_e32 v55, v55, v183
	v_mul_f32_e32 v176, 0xbfb8aa3b, v56
	v_mul_f32_e32 v177, 0xbfb8aa3b, v57
	v_mul_f32_e32 v178, 0xbfb8aa3b, v58
	v_mul_f32_e32 v179, 0xbfb8aa3b, v59
	v_mul_f32_e32 v180, 0xbfb8aa3b, v60
	v_mul_f32_e32 v181, 0xbfb8aa3b, v61
	v_mul_f32_e32 v182, 0xbfb8aa3b, v62
	v_mul_f32_e32 v183, 0xbfb8aa3b, v63
	v_exp_f32_e32 v176, v176
	v_exp_f32_e32 v177, v177
	v_exp_f32_e32 v178, v178
	v_exp_f32_e32 v179, v179
	v_exp_f32_e32 v180, v180
	v_exp_f32_e32 v181, v181
	v_exp_f32_e32 v182, v182
	v_exp_f32_e32 v183, v183
	v_add_f32_e32 v176, 1.0, v176
	v_add_f32_e32 v177, 1.0, v177
	v_add_f32_e32 v178, 1.0, v178
	v_add_f32_e32 v179, 1.0, v179
	v_add_f32_e32 v180, 1.0, v180
	v_add_f32_e32 v181, 1.0, v181
	v_add_f32_e32 v182, 1.0, v182
	v_add_f32_e32 v183, 1.0, v183
	v_rcp_f32_e32 v176, v176
	v_rcp_f32_e32 v177, v177
	v_rcp_f32_e32 v178, v178
	v_rcp_f32_e32 v179, v179
	v_rcp_f32_e32 v180, v180
	v_rcp_f32_e32 v181, v181
	v_rcp_f32_e32 v182, v182
	v_rcp_f32_e32 v183, v183
	v_mul_f32_e32 v56, v56, v176
	v_mul_f32_e32 v57, v57, v177
	v_mul_f32_e32 v58, v58, v178
	v_mul_f32_e32 v59, v59, v179
	v_mul_f32_e32 v60, v60, v180
	v_mul_f32_e32 v61, v61, v181
	v_mul_f32_e32 v62, v62, v182
	v_mul_f32_e32 v63, v63, v183
.Le1_nosilu0:
	ds_write_b128 v129, v[64:67]
	ds_write_b128 v129, v[68:71] offset:32
	ds_write_b128 v129, v[72:75] offset:64
	ds_write_b128 v129, v[76:79] offset:96
	ds_write_b128 v129, v[48:51] offset:128
	ds_write_b128 v129, v[52:55] offset:160
	ds_write_b128 v129, v[56:59] offset:192
	ds_write_b128 v129, v[60:63] offset:224
	ds_read_b128 v[184:187], v139 offset:0
	ds_read_b128 v[188:191], v139 offset:16
	ds_read_b128 v[220:223], v139 offset:2176
	ds_read_b128 v[224:227], v139 offset:2192
	ds_read_b128 v[228:231], v139 offset:4352
	ds_read_b128 v[232:235], v139 offset:4368
	ds_read_b128 v[236:239], v139 offset:6528
	ds_read_b128 v[240:243], v139 offset:6544
	s_waitcnt lgkmcnt(6)
	v_cvt_pk_bf16_f32 v184, v184, v185
	v_cvt_pk_bf16_f32 v185, v186, v187
	v_cvt_pk_bf16_f32 v186, v188, v189
	v_cvt_pk_bf16_f32 v187, v190, v191
	global_store_dwordx4 v172, v[184:187], s[66:67]
	s_waitcnt lgkmcnt(4)
	v_cvt_pk_bf16_f32 v220, v220, v221
	v_cvt_pk_bf16_f32 v221, v222, v223
	v_cvt_pk_bf16_f32 v222, v224, v225
	v_cvt_pk_bf16_f32 v223, v226, v227
	global_store_dwordx4 v173, v[220:223], s[66:67]
	s_waitcnt lgkmcnt(2)
	v_cvt_pk_bf16_f32 v228, v228, v229
	v_cvt_pk_bf16_f32 v229, v230, v231
	v_cvt_pk_bf16_f32 v230, v232, v233
	v_cvt_pk_bf16_f32 v231, v234, v235
	global_store_dwordx4 v174, v[228:231], s[66:67]
	s_waitcnt lgkmcnt(0)
	v_cvt_pk_bf16_f32 v236, v236, v237
	v_cvt_pk_bf16_f32 v237, v238, v239
	v_cvt_pk_bf16_f32 v238, v240, v241
	v_cvt_pk_bf16_f32 v239, v242, v243
	global_store_dwordx4 v175, v[236:239], s[66:67]
	s_add_u32 s66, s66, 0x2c000
	s_addc_u32 s67, s67, 0
	v_pk_mul_f32 v[16:17], v[16:17], v[134:135] op_sel_hi:[1,0]
	v_pk_mul_f32 v[18:19], v[18:19], v[134:135] op_sel_hi:[1,0]
	v_pk_mul_f32 v[20:21], v[20:21], v[134:135] op_sel_hi:[1,0]
	v_pk_mul_f32 v[22:23], v[22:23], v[134:135] op_sel_hi:[1,0]
	v_pk_mul_f32 v[24:25], v[24:25], v[134:135] op_sel_hi:[1,0]
	v_pk_mul_f32 v[26:27], v[26:27], v[134:135] op_sel_hi:[1,0]
	v_pk_mul_f32 v[28:29], v[28:29], v[134:135] op_sel_hi:[1,0]
	v_pk_mul_f32 v[30:31], v[30:31], v[134:135] op_sel_hi:[1,0]
	v_pk_mul_f32 v[0:1], v[0:1], v[134:135] op_sel_hi:[1,0]
	v_pk_mul_f32 v[2:3], v[2:3], v[134:135] op_sel_hi:[1,0]
	v_pk_mul_f32 v[4:5], v[4:5], v[134:135] op_sel_hi:[1,0]
	v_pk_mul_f32 v[6:7], v[6:7], v[134:135] op_sel_hi:[1,0]
	v_pk_mul_f32 v[8:9], v[8:9], v[134:135] op_sel_hi:[1,0]
	v_pk_mul_f32 v[10:11], v[10:11], v[134:135] op_sel_hi:[1,0]
	v_pk_mul_f32 v[12:13], v[12:13], v[134:135] op_sel_hi:[1,0]
	v_pk_mul_f32 v[14:15], v[14:15], v[134:135] op_sel_hi:[1,0]
	s_cmp_eq_u32 s69, 0
	s_cbranch_scc1 .Le1_nosilu1
	v_mul_f32_e32 v176, 0xbfb8aa3b, v16
	v_mul_f32_e32 v177, 0xbfb8aa3b, v17
	v_mul_f32_e32 v178, 0xbfb8aa3b, v18
	v_mul_f32_e32 v179, 0xbfb8aa3b, v19
	v_mul_f32_e32 v180, 0xbfb8aa3b, v20
	v_mul_f32_e32 v181, 0xbfb8aa3b, v21
	v_mul_f32_e32 v182, 0xbfb8aa3b, v22
	v_mul_f32_e32 v183, 0xbfb8aa3b, v23
	v_exp_f32_e32 v176, v176
	v_exp_f32_e32 v177, v177
	v_exp_f32_e32 v178, v178
	v_exp_f32_e32 v179, v179
	v_exp_f32_e32 v180, v180
	v_exp_f32_e32 v181, v181
	v_exp_f32_e32 v182, v182
	v_exp_f32_e32 v183, v183
	v_add_f32_e32 v176, 1.0, v176
	v_add_f32_e32 v177, 1.0, v177
	v_add_f32_e32 v178, 1.0, v178
	v_add_f32_e32 v179, 1.0, v179
	v_add_f32_e32 v180, 1.0, v180
	v_add_f32_e32 v181, 1.0, v181
	v_add_f32_e32 v182, 1.0, v182
	v_add_f32_e32 v183, 1.0, v183
	v_rcp_f32_e32 v176, v176
	v_rcp_f32_e32 v177, v177
	v_rcp_f32_e32 v178, v178
	v_rcp_f32_e32 v179, v179
	v_rcp_f32_e32 v180, v180
	v_rcp_f32_e32 v181, v181
	v_rcp_f32_e32 v182, v182
	v_rcp_f32_e32 v183, v183
	v_mul_f32_e32 v16, v16, v176
	v_mul_f32_e32 v17, v17, v177
	v_mul_f32_e32 v18, v18, v178
	v_mul_f32_e32 v19, v19, v179
	v_mul_f32_e32 v20, v20, v180
	v_mul_f32_e32 v21, v21, v181
	v_mul_f32_e32 v22, v22, v182
	v_mul_f32_e32 v23, v23, v183
	v_mul_f32_e32 v176, 0xbfb8aa3b, v24
	v_mul_f32_e32 v177, 0xbfb8aa3b, v25
	v_mul_f32_e32 v178, 0xbfb8aa3b, v26
	v_mul_f32_e32 v179, 0xbfb8aa3b, v27
	v_mul_f32_e32 v180, 0xbfb8aa3b, v28
	v_mul_f32_e32 v181, 0xbfb8aa3b, v29
	v_mul_f32_e32 v182, 0xbfb8aa3b, v30
	v_mul_f32_e32 v183, 0xbfb8aa3b, v31
	v_exp_f32_e32 v176, v176
	v_exp_f32_e32 v177, v177
	v_exp_f32_e32 v178, v178
	v_exp_f32_e32 v179, v179
	v_exp_f32_e32 v180, v180
	v_exp_f32_e32 v181, v181
	v_exp_f32_e32 v182, v182
	v_exp_f32_e32 v183, v183
	v_add_f32_e32 v176, 1.0, v176
	v_add_f32_e32 v177, 1.0, v177
	v_add_f32_e32 v178, 1.0, v178
	v_add_f32_e32 v179, 1.0, v179
	v_add_f32_e32 v180, 1.0, v180
	v_add_f32_e32 v181, 1.0, v181
	v_add_f32_e32 v182, 1.0, v182
	v_add_f32_e32 v183, 1.0, v183
	v_rcp_f32_e32 v176, v176
	v_rcp_f32_e32 v177, v177
	v_rcp_f32_e32 v178, v178
	v_rcp_f32_e32 v179, v179
	v_rcp_f32_e32 v180, v180
	v_rcp_f32_e32 v181, v181
	v_rcp_f32_e32 v182, v182
	v_rcp_f32_e32 v183, v183
	v_mul_f32_e32 v24, v24, v176
	v_mul_f32_e32 v25, v25, v177
	v_mul_f32_e32 v26, v26, v178
	v_mul_f32_e32 v27, v27, v179
	v_mul_f32_e32 v28, v28, v180
	v_mul_f32_e32 v29, v29, v181
	v_mul_f32_e32 v30, v30, v182
	v_mul_f32_e32 v31, v31, v183
	v_mul_f32_e32 v176, 0xbfb8aa3b, v0
	v_mul_f32_e32 v177, 0xbfb8aa3b, v1
	v_mul_f32_e32 v178, 0xbfb8aa3b, v2
	v_mul_f32_e32 v179, 0xbfb8aa3b, v3
	v_mul_f32_e32 v180, 0xbfb8aa3b, v4
	v_mul_f32_e32 v181, 0xbfb8aa3b, v5
	v_mul_f32_e32 v182, 0xbfb8aa3b, v6
	v_mul_f32_e32 v183, 0xbfb8aa3b, v7
	v_exp_f32_e32 v176, v176
	v_exp_f32_e32 v177, v177
	v_exp_f32_e32 v178, v178
	v_exp_f32_e32 v179, v179
	v_exp_f32_e32 v180, v180
	v_exp_f32_e32 v181, v181
	v_exp_f32_e32 v182, v182
	v_exp_f32_e32 v183, v183
	v_add_f32_e32 v176, 1.0, v176
	v_add_f32_e32 v177, 1.0, v177
	v_add_f32_e32 v178, 1.0, v178
	v_add_f32_e32 v179, 1.0, v179
	v_add_f32_e32 v180, 1.0, v180
	v_add_f32_e32 v181, 1.0, v181
	v_add_f32_e32 v182, 1.0, v182
	v_add_f32_e32 v183, 1.0, v183
	v_rcp_f32_e32 v176, v176
	v_rcp_f32_e32 v177, v177
	v_rcp_f32_e32 v178, v178
	v_rcp_f32_e32 v179, v179
	v_rcp_f32_e32 v180, v180
	v_rcp_f32_e32 v181, v181
	v_rcp_f32_e32 v182, v182
	v_rcp_f32_e32 v183, v183
	v_mul_f32_e32 v0, v0, v176
	v_mul_f32_e32 v1, v1, v177
	v_mul_f32_e32 v2, v2, v178
	v_mul_f32_e32 v3, v3, v179
	v_mul_f32_e32 v4, v4, v180
	v_mul_f32_e32 v5, v5, v181
	v_mul_f32_e32 v6, v6, v182
	v_mul_f32_e32 v7, v7, v183
	v_mul_f32_e32 v176, 0xbfb8aa3b, v8
	v_mul_f32_e32 v177, 0xbfb8aa3b, v9
	v_mul_f32_e32 v178, 0xbfb8aa3b, v10
	v_mul_f32_e32 v179, 0xbfb8aa3b, v11
	v_mul_f32_e32 v180, 0xbfb8aa3b, v12
	v_mul_f32_e32 v181, 0xbfb8aa3b, v13
	v_mul_f32_e32 v182, 0xbfb8aa3b, v14
	v_mul_f32_e32 v183, 0xbfb8aa3b, v15
	v_exp_f32_e32 v176, v176
	v_exp_f32_e32 v177, v177
	v_exp_f32_e32 v178, v178
	v_exp_f32_e32 v179, v179
	v_exp_f32_e32 v180, v180
	v_exp_f32_e32 v181, v181
	v_exp_f32_e32 v182, v182
	v_exp_f32_e32 v183, v183
	v_add_f32_e32 v176, 1.0, v176
	v_add_f32_e32 v177, 1.0, v177
	v_add_f32_e32 v178, 1.0, v178
	v_add_f32_e32 v179, 1.0, v179
	v_add_f32_e32 v180, 1.0, v180
	v_add_f32_e32 v181, 1.0, v181
	v_add_f32_e32 v182, 1.0, v182
	v_add_f32_e32 v183, 1.0, v183
	v_rcp_f32_e32 v176, v176
	v_rcp_f32_e32 v177, v177
	v_rcp_f32_e32 v178, v178
	v_rcp_f32_e32 v179, v179
	v_rcp_f32_e32 v180, v180
	v_rcp_f32_e32 v181, v181
	v_rcp_f32_e32 v182, v182
	v_rcp_f32_e32 v183, v183
	v_mul_f32_e32 v8, v8, v176
	v_mul_f32_e32 v9, v9, v177
	v_mul_f32_e32 v10, v10, v178
	v_mul_f32_e32 v11, v11, v179
	v_mul_f32_e32 v12, v12, v180
	v_mul_f32_e32 v13, v13, v181
	v_mul_f32_e32 v14, v14, v182
	v_mul_f32_e32 v15, v15, v183
.Le1_nosilu1:
	ds_write_b128 v129, v[16:19]
	ds_write_b128 v129, v[20:23] offset:32
	ds_write_b128 v129, v[24:27] offset:64
	ds_write_b128 v129, v[28:31] offset:96
	ds_write_b128 v129, v[0:3] offset:128
	ds_write_b128 v129, v[4:7] offset:160
	ds_write_b128 v129, v[8:11] offset:192
	ds_write_b128 v129, v[12:15] offset:224
	ds_read_b128 v[184:187], v139 offset:0
	ds_read_b128 v[188:191], v139 offset:16
	ds_read_b128 v[220:223], v139 offset:2176
	ds_read_b128 v[224:227], v139 offset:2192
	ds_read_b128 v[228:231], v139 offset:4352
	ds_read_b128 v[232:235], v139 offset:4368
	ds_read_b128 v[236:239], v139 offset:6528
	ds_read_b128 v[240:243], v139 offset:6544
	s_waitcnt lgkmcnt(6)
	v_cvt_pk_bf16_f32 v184, v184, v185
	v_cvt_pk_bf16_f32 v185, v186, v187
	v_cvt_pk_bf16_f32 v186, v188, v189
	v_cvt_pk_bf16_f32 v187, v190, v191
	global_store_dwordx4 v172, v[184:187], s[66:67]
	s_waitcnt lgkmcnt(4)
	v_cvt_pk_bf16_f32 v220, v220, v221
	v_cvt_pk_bf16_f32 v221, v222, v223
	v_cvt_pk_bf16_f32 v222, v224, v225
	v_cvt_pk_bf16_f32 v223, v226, v227
	global_store_dwordx4 v173, v[220:223], s[66:67]
	s_waitcnt lgkmcnt(2)
	v_cvt_pk_bf16_f32 v228, v228, v229
	v_cvt_pk_bf16_f32 v229, v230, v231
	v_cvt_pk_bf16_f32 v230, v232, v233
	v_cvt_pk_bf16_f32 v231, v234, v235
	global_store_dwordx4 v174, v[228:231], s[66:67]
	s_waitcnt lgkmcnt(0)
	v_cvt_pk_bf16_f32 v236, v236, v237
	v_cvt_pk_bf16_f32 v237, v238, v239
	v_cvt_pk_bf16_f32 v238, v240, v241
	v_cvt_pk_bf16_f32 v239, v242, v243
	global_store_dwordx4 v175, v[236:239], s[66:67]
	s_add_u32 s66, s66, 0x2c000
	s_addc_u32 s67, s67, 0
	s_cmp_lt_u32 s56, 0x80
	s_cbranch_scc0 .Le1_done
	v_pk_mul_f32 v[80:81], v[80:81], v[136:137] op_sel_hi:[1,0]
	v_pk_mul_f32 v[82:83], v[82:83], v[136:137] op_sel_hi:[1,0]
	v_pk_mul_f32 v[84:85], v[84:85], v[136:137] op_sel_hi:[1,0]
	v_pk_mul_f32 v[86:87], v[86:87], v[136:137] op_sel_hi:[1,0]
	v_pk_mul_f32 v[88:89], v[88:89], v[136:137] op_sel_hi:[1,0]
	v_pk_mul_f32 v[90:91], v[90:91], v[136:137] op_sel_hi:[1,0]
	v_pk_mul_f32 v[92:93], v[92:93], v[136:137] op_sel_hi:[1,0]
	v_pk_mul_f32 v[94:95], v[94:95], v[136:137] op_sel_hi:[1,0]
	v_pk_mul_f32 v[112:113], v[112:113], v[136:137] op_sel_hi:[1,0]
	v_pk_mul_f32 v[114:115], v[114:115], v[136:137] op_sel_hi:[1,0]
	v_pk_mul_f32 v[116:117], v[116:117], v[136:137] op_sel_hi:[1,0]
	v_pk_mul_f32 v[118:119], v[118:119], v[136:137] op_sel_hi:[1,0]
	v_pk_mul_f32 v[120:121], v[120:121], v[136:137] op_sel_hi:[1,0]
	v_pk_mul_f32 v[122:123], v[122:123], v[136:137] op_sel_hi:[1,0]
	v_pk_mul_f32 v[124:125], v[124:125], v[136:137] op_sel_hi:[1,0]
	v_pk_mul_f32 v[126:127], v[126:127], v[136:137] op_sel_hi:[1,0]
	s_cmp_eq_u32 s69, 0
	s_cbranch_scc1 .Le1_nosilu2
	v_mul_f32_e32 v176, 0xbfb8aa3b, v80
	v_mul_f32_e32 v177, 0xbfb8aa3b, v81
	v_mul_f32_e32 v178, 0xbfb8aa3b, v82
	v_mul_f32_e32 v179, 0xbfb8aa3b, v83
	v_mul_f32_e32 v180, 0xbfb8aa3b, v84
	v_mul_f32_e32 v181, 0xbfb8aa3b, v85
	v_mul_f32_e32 v182, 0xbfb8aa3b, v86
	v_mul_f32_e32 v183, 0xbfb8aa3b, v87
	v_exp_f32_e32 v176, v176
	v_exp_f32_e32 v177, v177
	v_exp_f32_e32 v178, v178
	v_exp_f32_e32 v179, v179
	v_exp_f32_e32 v180, v180
	v_exp_f32_e32 v181, v181
	v_exp_f32_e32 v182, v182
	v_exp_f32_e32 v183, v183
	v_add_f32_e32 v176, 1.0, v176
	v_add_f32_e32 v177, 1.0, v177
	v_add_f32_e32 v178, 1.0, v178
	v_add_f32_e32 v179, 1.0, v179
	v_add_f32_e32 v180, 1.0, v180
	v_add_f32_e32 v181, 1.0, v181
	v_add_f32_e32 v182, 1.0, v182
	v_add_f32_e32 v183, 1.0, v183
	v_rcp_f32_e32 v176, v176
	v_rcp_f32_e32 v177, v177
	v_rcp_f32_e32 v178, v178
	v_rcp_f32_e32 v179, v179
	v_rcp_f32_e32 v180, v180
	v_rcp_f32_e32 v181, v181
	v_rcp_f32_e32 v182, v182
	v_rcp_f32_e32 v183, v183
	v_mul_f32_e32 v80, v80, v176
	v_mul_f32_e32 v81, v81, v177
	v_mul_f32_e32 v82, v82, v178
	v_mul_f32_e32 v83, v83, v179
	v_mul_f32_e32 v84, v84, v180
	v_mul_f32_e32 v85, v85, v181
	v_mul_f32_e32 v86, v86, v182
	v_mul_f32_e32 v87, v87, v183
	v_mul_f32_e32 v176, 0xbfb8aa3b, v88
	v_mul_f32_e32 v177, 0xbfb8aa3b, v89
	v_mul_f32_e32 v178, 0xbfb8aa3b, v90
	v_mul_f32_e32 v179, 0xbfb8aa3b, v91
	v_mul_f32_e32 v180, 0xbfb8aa3b, v92
	v_mul_f32_e32 v181, 0xbfb8aa3b, v93
	v_mul_f32_e32 v182, 0xbfb8aa3b, v94
	v_mul_f32_e32 v183, 0xbfb8aa3b, v95
	v_exp_f32_e32 v176, v176
	v_exp_f32_e32 v177, v177
	v_exp_f32_e32 v178, v178
	v_exp_f32_e32 v179, v179
	v_exp_f32_e32 v180, v180
	v_exp_f32_e32 v181, v181
	v_exp_f32_e32 v182, v182
	v_exp_f32_e32 v183, v183
	v_add_f32_e32 v176, 1.0, v176
	v_add_f32_e32 v177, 1.0, v177
	v_add_f32_e32 v178, 1.0, v178
	v_add_f32_e32 v179, 1.0, v179
	v_add_f32_e32 v180, 1.0, v180
	v_add_f32_e32 v181, 1.0, v181
	v_add_f32_e32 v182, 1.0, v182
	v_add_f32_e32 v183, 1.0, v183
	v_rcp_f32_e32 v176, v176
	v_rcp_f32_e32 v177, v177
	v_rcp_f32_e32 v178, v178
	v_rcp_f32_e32 v179, v179
	v_rcp_f32_e32 v180, v180
	v_rcp_f32_e32 v181, v181
	v_rcp_f32_e32 v182, v182
	v_rcp_f32_e32 v183, v183
	v_mul_f32_e32 v88, v88, v176
	v_mul_f32_e32 v89, v89, v177
	v_mul_f32_e32 v90, v90, v178
	v_mul_f32_e32 v91, v91, v179
	v_mul_f32_e32 v92, v92, v180
	v_mul_f32_e32 v93, v93, v181
	v_mul_f32_e32 v94, v94, v182
	v_mul_f32_e32 v95, v95, v183
	v_mul_f32_e32 v176, 0xbfb8aa3b, v112
	v_mul_f32_e32 v177, 0xbfb8aa3b, v113
	v_mul_f32_e32 v178, 0xbfb8aa3b, v114
	v_mul_f32_e32 v179, 0xbfb8aa3b, v115
	v_mul_f32_e32 v180, 0xbfb8aa3b, v116
	v_mul_f32_e32 v181, 0xbfb8aa3b, v117
	v_mul_f32_e32 v182, 0xbfb8aa3b, v118
	v_mul_f32_e32 v183, 0xbfb8aa3b, v119
	v_exp_f32_e32 v176, v176
	v_exp_f32_e32 v177, v177
	v_exp_f32_e32 v178, v178
	v_exp_f32_e32 v179, v179
	v_exp_f32_e32 v180, v180
	v_exp_f32_e32 v181, v181
	v_exp_f32_e32 v182, v182
	v_exp_f32_e32 v183, v183
	v_add_f32_e32 v176, 1.0, v176
	v_add_f32_e32 v177, 1.0, v177
	v_add_f32_e32 v178, 1.0, v178
	v_add_f32_e32 v179, 1.0, v179
	v_add_f32_e32 v180, 1.0, v180
	v_add_f32_e32 v181, 1.0, v181
	v_add_f32_e32 v182, 1.0, v182
	v_add_f32_e32 v183, 1.0, v183
	v_rcp_f32_e32 v176, v176
	v_rcp_f32_e32 v177, v177
	v_rcp_f32_e32 v178, v178
	v_rcp_f32_e32 v179, v179
	v_rcp_f32_e32 v180, v180
	v_rcp_f32_e32 v181, v181
	v_rcp_f32_e32 v182, v182
	v_rcp_f32_e32 v183, v183
	v_mul_f32_e32 v112, v112, v176
	v_mul_f32_e32 v113, v113, v177
	v_mul_f32_e32 v114, v114, v178
	v_mul_f32_e32 v115, v115, v179
	v_mul_f32_e32 v116, v116, v180
	v_mul_f32_e32 v117, v117, v181
	v_mul_f32_e32 v118, v118, v182
	v_mul_f32_e32 v119, v119, v183
	v_mul_f32_e32 v176, 0xbfb8aa3b, v120
	v_mul_f32_e32 v177, 0xbfb8aa3b, v121
	v_mul_f32_e32 v178, 0xbfb8aa3b, v122
	v_mul_f32_e32 v179, 0xbfb8aa3b, v123
	v_mul_f32_e32 v180, 0xbfb8aa3b, v124
	v_mul_f32_e32 v181, 0xbfb8aa3b, v125
	v_mul_f32_e32 v182, 0xbfb8aa3b, v126
	v_mul_f32_e32 v183, 0xbfb8aa3b, v127
	v_exp_f32_e32 v176, v176
	v_exp_f32_e32 v177, v177
	v_exp_f32_e32 v178, v178
	v_exp_f32_e32 v179, v179
	v_exp_f32_e32 v180, v180
	v_exp_f32_e32 v181, v181
	v_exp_f32_e32 v182, v182
	v_exp_f32_e32 v183, v183
	v_add_f32_e32 v176, 1.0, v176
	v_add_f32_e32 v177, 1.0, v177
	v_add_f32_e32 v178, 1.0, v178
	v_add_f32_e32 v179, 1.0, v179
	v_add_f32_e32 v180, 1.0, v180
	v_add_f32_e32 v181, 1.0, v181
	v_add_f32_e32 v182, 1.0, v182
	v_add_f32_e32 v183, 1.0, v183
	v_rcp_f32_e32 v176, v176
	v_rcp_f32_e32 v177, v177
	v_rcp_f32_e32 v178, v178
	v_rcp_f32_e32 v179, v179
	v_rcp_f32_e32 v180, v180
	v_rcp_f32_e32 v181, v181
	v_rcp_f32_e32 v182, v182
	v_rcp_f32_e32 v183, v183
	v_mul_f32_e32 v120, v120, v176
	v_mul_f32_e32 v121, v121, v177
	v_mul_f32_e32 v122, v122, v178
	v_mul_f32_e32 v123, v123, v179
	v_mul_f32_e32 v124, v124, v180
	v_mul_f32_e32 v125, v125, v181
	v_mul_f32_e32 v126, v126, v182
	v_mul_f32_e32 v127, v127, v183
.Le1_nosilu2:
	ds_write_b128 v129, v[80:83]
	ds_write_b128 v129, v[84:87] offset:32
	ds_write_b128 v129, v[88:91] offset:64
	ds_write_b128 v129, v[92:95] offset:96
	ds_write_b128 v129, v[112:115] offset:128
	ds_write_b128 v129, v[116:119] offset:160
	ds_write_b128 v129, v[120:123] offset:192
	ds_write_b128 v129, v[124:127] offset:224
	ds_read_b128 v[184:187], v139 offset:0
	ds_read_b128 v[188:191], v139 offset:16
	ds_read_b128 v[220:223], v139 offset:2176
	ds_read_b128 v[224:227], v139 offset:2192
	ds_read_b128 v[228:231], v139 offset:4352
	ds_read_b128 v[232:235], v139 offset:4368
	ds_read_b128 v[236:239], v139 offset:6528
	ds_read_b128 v[240:243], v139 offset:6544
	s_waitcnt lgkmcnt(6)
	v_cvt_pk_bf16_f32 v184, v184, v185
	v_cvt_pk_bf16_f32 v185, v186, v187
	v_cvt_pk_bf16_f32 v186, v188, v189
	v_cvt_pk_bf16_f32 v187, v190, v191
	global_store_dwordx4 v172, v[184:187], s[66:67]
	s_waitcnt lgkmcnt(4)
	v_cvt_pk_bf16_f32 v220, v220, v221
	v_cvt_pk_bf16_f32 v221, v222, v223
	v_cvt_pk_bf16_f32 v222, v224, v225
	v_cvt_pk_bf16_f32 v223, v226, v227
	global_store_dwordx4 v173, v[220:223], s[66:67]
	s_waitcnt lgkmcnt(2)
	v_cvt_pk_bf16_f32 v228, v228, v229
	v_cvt_pk_bf16_f32 v229, v230, v231
	v_cvt_pk_bf16_f32 v230, v232, v233
	v_cvt_pk_bf16_f32 v231, v234, v235
	global_store_dwordx4 v174, v[228:231], s[66:67]
	s_waitcnt lgkmcnt(0)
	v_cvt_pk_bf16_f32 v236, v236, v237
	v_cvt_pk_bf16_f32 v237, v238, v239
	v_cvt_pk_bf16_f32 v238, v240, v241
	v_cvt_pk_bf16_f32 v239, v242, v243
	global_store_dwordx4 v175, v[236:239], s[66:67]
	s_add_u32 s66, s66, 0x2c000
	s_addc_u32 s67, s67, 0
	v_pk_mul_f32 v[32:33], v[32:33], v[138:139] op_sel_hi:[1,0]
	v_pk_mul_f32 v[34:35], v[34:35], v[138:139] op_sel_hi:[1,0]
	v_pk_mul_f32 v[36:37], v[36:37], v[138:139] op_sel_hi:[1,0]
	v_pk_mul_f32 v[38:39], v[38:39], v[138:139] op_sel_hi:[1,0]
	v_pk_mul_f32 v[40:41], v[40:41], v[138:139] op_sel_hi:[1,0]
	v_pk_mul_f32 v[42:43], v[42:43], v[138:139] op_sel_hi:[1,0]
	v_pk_mul_f32 v[44:45], v[44:45], v[138:139] op_sel_hi:[1,0]
	v_pk_mul_f32 v[46:47], v[46:47], v[138:139] op_sel_hi:[1,0]
	v_pk_mul_f32 v[96:97], v[96:97], v[138:139] op_sel_hi:[1,0]
	v_pk_mul_f32 v[98:99], v[98:99], v[138:139] op_sel_hi:[1,0]
	v_pk_mul_f32 v[100:101], v[100:101], v[138:139] op_sel_hi:[1,0]
	v_pk_mul_f32 v[102:103], v[102:103], v[138:139] op_sel_hi:[1,0]
	v_pk_mul_f32 v[104:105], v[104:105], v[138:139] op_sel_hi:[1,0]
	v_pk_mul_f32 v[106:107], v[106:107], v[138:139] op_sel_hi:[1,0]
	v_pk_mul_f32 v[108:109], v[108:109], v[138:139] op_sel_hi:[1,0]
	v_pk_mul_f32 v[110:111], v[110:111], v[138:139] op_sel_hi:[1,0]
	s_cmp_eq_u32 s69, 0
	s_cbranch_scc1 .Le1_nosilu3
	v_mul_f32_e32 v176, 0xbfb8aa3b, v32
	v_mul_f32_e32 v177, 0xbfb8aa3b, v33
	v_mul_f32_e32 v178, 0xbfb8aa3b, v34
	v_mul_f32_e32 v179, 0xbfb8aa3b, v35
	v_mul_f32_e32 v180, 0xbfb8aa3b, v36
	v_mul_f32_e32 v181, 0xbfb8aa3b, v37
	v_mul_f32_e32 v182, 0xbfb8aa3b, v38
	v_mul_f32_e32 v183, 0xbfb8aa3b, v39
	v_exp_f32_e32 v176, v176
	v_exp_f32_e32 v177, v177
	v_exp_f32_e32 v178, v178
	v_exp_f32_e32 v179, v179
	v_exp_f32_e32 v180, v180
	v_exp_f32_e32 v181, v181
	v_exp_f32_e32 v182, v182
	v_exp_f32_e32 v183, v183
	v_add_f32_e32 v176, 1.0, v176
	v_add_f32_e32 v177, 1.0, v177
	v_add_f32_e32 v178, 1.0, v178
	v_add_f32_e32 v179, 1.0, v179
	v_add_f32_e32 v180, 1.0, v180
	v_add_f32_e32 v181, 1.0, v181
	v_add_f32_e32 v182, 1.0, v182
	v_add_f32_e32 v183, 1.0, v183
	v_rcp_f32_e32 v176, v176
	v_rcp_f32_e32 v177, v177
	v_rcp_f32_e32 v178, v178
	v_rcp_f32_e32 v179, v179
	v_rcp_f32_e32 v180, v180
	v_rcp_f32_e32 v181, v181
	v_rcp_f32_e32 v182, v182
	v_rcp_f32_e32 v183, v183
	v_mul_f32_e32 v32, v32, v176
	v_mul_f32_e32 v33, v33, v177
	v_mul_f32_e32 v34, v34, v178
	v_mul_f32_e32 v35, v35, v179
	v_mul_f32_e32 v36, v36, v180
	v_mul_f32_e32 v37, v37, v181
	v_mul_f32_e32 v38, v38, v182
	v_mul_f32_e32 v39, v39, v183
	v_mul_f32_e32 v176, 0xbfb8aa3b, v40
	v_mul_f32_e32 v177, 0xbfb8aa3b, v41
	v_mul_f32_e32 v178, 0xbfb8aa3b, v42
	v_mul_f32_e32 v179, 0xbfb8aa3b, v43
	v_mul_f32_e32 v180, 0xbfb8aa3b, v44
	v_mul_f32_e32 v181, 0xbfb8aa3b, v45
	v_mul_f32_e32 v182, 0xbfb8aa3b, v46
	v_mul_f32_e32 v183, 0xbfb8aa3b, v47
	v_exp_f32_e32 v176, v176
	v_exp_f32_e32 v177, v177
	v_exp_f32_e32 v178, v178
	v_exp_f32_e32 v179, v179
	v_exp_f32_e32 v180, v180
	v_exp_f32_e32 v181, v181
	v_exp_f32_e32 v182, v182
	v_exp_f32_e32 v183, v183
	v_add_f32_e32 v176, 1.0, v176
	v_add_f32_e32 v177, 1.0, v177
	v_add_f32_e32 v178, 1.0, v178
	v_add_f32_e32 v179, 1.0, v179
	v_add_f32_e32 v180, 1.0, v180
	v_add_f32_e32 v181, 1.0, v181
	v_add_f32_e32 v182, 1.0, v182
	v_add_f32_e32 v183, 1.0, v183
	v_rcp_f32_e32 v176, v176
	v_rcp_f32_e32 v177, v177
	v_rcp_f32_e32 v178, v178
	v_rcp_f32_e32 v179, v179
	v_rcp_f32_e32 v180, v180
	v_rcp_f32_e32 v181, v181
	v_rcp_f32_e32 v182, v182
	v_rcp_f32_e32 v183, v183
	v_mul_f32_e32 v40, v40, v176
	v_mul_f32_e32 v41, v41, v177
	v_mul_f32_e32 v42, v42, v178
	v_mul_f32_e32 v43, v43, v179
	v_mul_f32_e32 v44, v44, v180
	v_mul_f32_e32 v45, v45, v181
	v_mul_f32_e32 v46, v46, v182
	v_mul_f32_e32 v47, v47, v183
	v_mul_f32_e32 v176, 0xbfb8aa3b, v96
	v_mul_f32_e32 v177, 0xbfb8aa3b, v97
	v_mul_f32_e32 v178, 0xbfb8aa3b, v98
	v_mul_f32_e32 v179, 0xbfb8aa3b, v99
	v_mul_f32_e32 v180, 0xbfb8aa3b, v100
	v_mul_f32_e32 v181, 0xbfb8aa3b, v101
	v_mul_f32_e32 v182, 0xbfb8aa3b, v102
	v_mul_f32_e32 v183, 0xbfb8aa3b, v103
	v_exp_f32_e32 v176, v176
	v_exp_f32_e32 v177, v177
	v_exp_f32_e32 v178, v178
	v_exp_f32_e32 v179, v179
	v_exp_f32_e32 v180, v180
	v_exp_f32_e32 v181, v181
	v_exp_f32_e32 v182, v182
	v_exp_f32_e32 v183, v183
	v_add_f32_e32 v176, 1.0, v176
	v_add_f32_e32 v177, 1.0, v177
	v_add_f32_e32 v178, 1.0, v178
	v_add_f32_e32 v179, 1.0, v179
	v_add_f32_e32 v180, 1.0, v180
	v_add_f32_e32 v181, 1.0, v181
	v_add_f32_e32 v182, 1.0, v182
	v_add_f32_e32 v183, 1.0, v183
	v_rcp_f32_e32 v176, v176
	v_rcp_f32_e32 v177, v177
	v_rcp_f32_e32 v178, v178
	v_rcp_f32_e32 v179, v179
	v_rcp_f32_e32 v180, v180
	v_rcp_f32_e32 v181, v181
	v_rcp_f32_e32 v182, v182
	v_rcp_f32_e32 v183, v183
	v_mul_f32_e32 v96, v96, v176
	v_mul_f32_e32 v97, v97, v177
	v_mul_f32_e32 v98, v98, v178
	v_mul_f32_e32 v99, v99, v179
	v_mul_f32_e32 v100, v100, v180
	v_mul_f32_e32 v101, v101, v181
	v_mul_f32_e32 v102, v102, v182
	v_mul_f32_e32 v103, v103, v183
	v_mul_f32_e32 v176, 0xbfb8aa3b, v104
	v_mul_f32_e32 v177, 0xbfb8aa3b, v105
	v_mul_f32_e32 v178, 0xbfb8aa3b, v106
	v_mul_f32_e32 v179, 0xbfb8aa3b, v107
	v_mul_f32_e32 v180, 0xbfb8aa3b, v108
	v_mul_f32_e32 v181, 0xbfb8aa3b, v109
	v_mul_f32_e32 v182, 0xbfb8aa3b, v110
	v_mul_f32_e32 v183, 0xbfb8aa3b, v111
	v_exp_f32_e32 v176, v176
	v_exp_f32_e32 v177, v177
	v_exp_f32_e32 v178, v178
	v_exp_f32_e32 v179, v179
	v_exp_f32_e32 v180, v180
	v_exp_f32_e32 v181, v181
	v_exp_f32_e32 v182, v182
	v_exp_f32_e32 v183, v183
	v_add_f32_e32 v176, 1.0, v176
	v_add_f32_e32 v177, 1.0, v177
	v_add_f32_e32 v178, 1.0, v178
	v_add_f32_e32 v179, 1.0, v179
	v_add_f32_e32 v180, 1.0, v180
	v_add_f32_e32 v181, 1.0, v181
	v_add_f32_e32 v182, 1.0, v182
	v_add_f32_e32 v183, 1.0, v183
	v_rcp_f32_e32 v176, v176
	v_rcp_f32_e32 v177, v177
	v_rcp_f32_e32 v178, v178
	v_rcp_f32_e32 v179, v179
	v_rcp_f32_e32 v180, v180
	v_rcp_f32_e32 v181, v181
	v_rcp_f32_e32 v182, v182
	v_rcp_f32_e32 v183, v183
	v_mul_f32_e32 v104, v104, v176
	v_mul_f32_e32 v105, v105, v177
	v_mul_f32_e32 v106, v106, v178
	v_mul_f32_e32 v107, v107, v179
	v_mul_f32_e32 v108, v108, v180
	v_mul_f32_e32 v109, v109, v181
	v_mul_f32_e32 v110, v110, v182
	v_mul_f32_e32 v111, v111, v183
.Le1_nosilu3:
	ds_write_b128 v129, v[32:35]
	ds_write_b128 v129, v[36:39] offset:32
	ds_write_b128 v129, v[40:43] offset:64
	ds_write_b128 v129, v[44:47] offset:96
	ds_write_b128 v129, v[96:99] offset:128
	ds_write_b128 v129, v[100:103] offset:160
	ds_write_b128 v129, v[104:107] offset:192
	ds_write_b128 v129, v[108:111] offset:224
	ds_read_b128 v[184:187], v139 offset:0
	ds_read_b128 v[188:191], v139 offset:16
	ds_read_b128 v[220:223], v139 offset:2176
	ds_read_b128 v[224:227], v139 offset:2192
	ds_read_b128 v[228:231], v139 offset:4352
	ds_read_b128 v[232:235], v139 offset:4368
	ds_read_b128 v[236:239], v139 offset:6528
	ds_read_b128 v[240:243], v139 offset:6544
	s_waitcnt lgkmcnt(6)
	v_cvt_pk_bf16_f32 v184, v184, v185
	v_cvt_pk_bf16_f32 v185, v186, v187
	v_cvt_pk_bf16_f32 v186, v188, v189
	v_cvt_pk_bf16_f32 v187, v190, v191
	global_store_dwordx4 v172, v[184:187], s[66:67]
	s_waitcnt lgkmcnt(4)
	v_cvt_pk_bf16_f32 v220, v220, v221
	v_cvt_pk_bf16_f32 v221, v222, v223
	v_cvt_pk_bf16_f32 v222, v224, v225
	v_cvt_pk_bf16_f32 v223, v226, v227
	global_store_dwordx4 v173, v[220:223], s[66:67]
	s_waitcnt lgkmcnt(2)
	v_cvt_pk_bf16_f32 v228, v228, v229
	v_cvt_pk_bf16_f32 v229, v230, v231
	v_cvt_pk_bf16_f32 v230, v232, v233
	v_cvt_pk_bf16_f32 v231, v234, v235
	global_store_dwordx4 v174, v[228:231], s[66:67]
	s_waitcnt lgkmcnt(0)
	v_cvt_pk_bf16_f32 v236, v236, v237
	v_cvt_pk_bf16_f32 v237, v238, v239
	v_cvt_pk_bf16_f32 v238, v240, v241
	v_cvt_pk_bf16_f32 v239, v242, v243
	global_store_dwordx4 v175, v[236:239], s[66:67]
.Le1_done:
	s_mov_b64 s[0:1], exec
	s_branch .LBB0_141
